# gate/up K-loop: LDS-DMA pieces addressed as SGPR base + 32-bit VGPR offset, 16 v_lshl_add_u64 per iteration removed
# speedup vs baseline: 1.0018x; 1.0018x over previous
.LBB0_544:
	ds_read_b128 v[144:147], v155
	ds_read_b128 v[148:151], v155 offset:1024
	ds_read_b128 v[160:163], v155 offset:2048
	ds_read_b128 v[164:167], v155 offset:3072
	ds_read_b128 v[170:173], v156
	ds_read_b128 v[174:177], v156 offset:1024
	ds_read_b128 v[178:181], v156 offset:2048
	ds_read_b128 v[182:185], v156 offset:3072
	s_add_u32 s40, s38, 0xfffc0080
	s_addc_u32 s41, s39, -1
	s_cmp_eq_u32 s63, 12
	s_cselect_b32 s43, s19, s41
	s_cselect_b32 s42, s59, s40
	s_cselect_b32 s41, s21, s62
	s_cselect_b32 s40, s60, s61
	s_add_i32 m0, s37, 0xc000
	ds_read_b128 v[186:189], v157
	ds_read_b128 v[190:193], v157 offset:1024
	ds_read_b128 v[194:197], v157 offset:2048
	ds_read_b128 v[198:201], v157 offset:3072
	ds_read_b128 v[202:205], v157 offset:4096
	ds_read_b128 v[206:209], v157 offset:5120
	ds_read_b128 v[210:213], v157 offset:6144
	ds_read_b128 v[214:217], v157 offset:7168
	global_load_lds_dwordx4 v136, s[38:39]
	s_add_i32 m0, s37, 0xe000
	s_nop 0
	global_load_lds_dwordx4 v138, s[38:39]
	s_waitcnt vmcnt(8)
	s_waitcnt lgkmcnt(0)
	s_barrier
	s_setprio 1
	s_waitcnt lgkmcnt(0)
	v_mfma_f32_16x16x32_bf16 v[124:127], v[144:147], v[186:189], v[124:127]
	v_mfma_f32_16x16x32_bf16 v[120:123], v[160:163], v[186:189], v[120:123]
	v_mfma_f32_16x16x32_bf16 v[108:111], v[144:147], v[194:197], v[108:111]
	v_mfma_f32_16x16x32_bf16 v[104:107], v[160:163], v[194:197], v[104:107]
	v_mfma_f32_16x16x32_bf16 v[92:95], v[144:147], v[202:205], v[92:95]
	v_mfma_f32_16x16x32_bf16 v[88:91], v[160:163], v[202:205], v[88:91]
	v_mfma_f32_16x16x32_bf16 v[76:79], v[144:147], v[210:213], v[76:79]
	v_mfma_f32_16x16x32_bf16 v[72:75], v[160:163], v[210:213], v[72:75]
	v_mfma_f32_16x16x32_bf16 v[124:127], v[148:151], v[190:193], v[124:127]
	v_mfma_f32_16x16x32_bf16 v[120:123], v[164:167], v[190:193], v[120:123]
	v_mfma_f32_16x16x32_bf16 v[108:111], v[148:151], v[198:201], v[108:111]
	v_mfma_f32_16x16x32_bf16 v[104:107], v[164:167], v[198:201], v[104:107]
	v_mfma_f32_16x16x32_bf16 v[92:95], v[148:151], v[206:209], v[92:95]
	v_mfma_f32_16x16x32_bf16 v[88:91], v[164:167], v[206:209], v[88:91]
	v_mfma_f32_16x16x32_bf16 v[76:79], v[148:151], v[214:217], v[76:79]
	v_mfma_f32_16x16x32_bf16 v[72:75], v[164:167], v[214:217], v[72:75]
	s_setprio 0
	s_setprio 1
	v_mfma_f32_16x16x32_bf16 v[116:119], v[170:173], v[186:189], v[116:119]
	v_mfma_f32_16x16x32_bf16 v[112:115], v[178:181], v[186:189], v[112:115]
	v_mfma_f32_16x16x32_bf16 v[100:103], v[170:173], v[194:197], v[100:103]
	v_mfma_f32_16x16x32_bf16 v[96:99], v[178:181], v[194:197], v[96:99]
	v_mfma_f32_16x16x32_bf16 v[84:87], v[170:173], v[202:205], v[84:87]
	v_mfma_f32_16x16x32_bf16 v[80:83], v[178:181], v[202:205], v[80:83]
	v_mfma_f32_16x16x32_bf16 v[68:71], v[170:173], v[210:213], v[68:71]
	v_mfma_f32_16x16x32_bf16 v[64:67], v[178:181], v[210:213], v[64:67]
	v_mfma_f32_16x16x32_bf16 v[116:119], v[174:177], v[190:193], v[116:119]
	v_mfma_f32_16x16x32_bf16 v[112:115], v[182:185], v[190:193], v[112:115]
	v_mfma_f32_16x16x32_bf16 v[100:103], v[174:177], v[198:201], v[100:103]
	v_mfma_f32_16x16x32_bf16 v[96:99], v[182:185], v[198:201], v[96:99]
	v_mfma_f32_16x16x32_bf16 v[84:87], v[174:177], v[206:209], v[84:87]
	v_mfma_f32_16x16x32_bf16 v[80:83], v[182:185], v[206:209], v[80:83]
	v_mfma_f32_16x16x32_bf16 v[68:71], v[174:177], v[214:217], v[68:71]
	v_mfma_f32_16x16x32_bf16 v[64:67], v[182:185], v[214:217], v[64:67]
	s_setprio 0
	s_barrier
	s_add_i32 s64, s56, s45
	s_mov_b32 m0, s64
	ds_read_b128 v[186:189], v157 offset:16384
	ds_read_b128 v[190:193], v157 offset:17408
	ds_read_b128 v[194:197], v157 offset:18432
	ds_read_b128 v[198:201], v157 offset:19456
	ds_read_b128 v[202:205], v157 offset:20480
	ds_read_b128 v[206:209], v157 offset:21504
	ds_read_b128 v[210:213], v157 offset:22528
	ds_read_b128 v[214:217], v157 offset:23552
	global_load_lds_dwordx4 v132, s[40:41]
	s_add_i32 m0, s64, 0x2000
	s_add_u32 s64, s40, 0x40000
	s_addc_u32 s65, s41, 0
	s_add_i32 s66, s57, s45
	global_load_lds_dwordx4 v128, s[40:41]
	s_mov_b32 m0, s66
	s_nop 0
	global_load_lds_dwordx4 v132, s[64:65]
	s_add_i32 m0, s66, 0x2000
	s_nop 0
	global_load_lds_dwordx4 v128, s[64:65]
	s_add_u32 vcc_lo, s42, s14
	s_addc_u32 vcc_hi, s43, s15
	s_mov_b32 m0, s37
	s_nop 0
	global_load_lds_dwordx4 v134, s[42:43]
	s_mov_b32 m0, s48
	s_nop 0
	global_load_lds_dwordx4 v130, s[42:43]
	s_waitcnt vmcnt(8)
	s_waitcnt lgkmcnt(0)
	s_barrier
	s_setprio 1
	s_waitcnt lgkmcnt(0)
	v_mfma_f32_16x16x32_bf16 v[60:63], v[144:147], v[186:189], v[60:63]
	v_mfma_f32_16x16x32_bf16 v[56:59], v[160:163], v[186:189], v[56:59]
	v_mfma_f32_16x16x32_bf16 v[44:47], v[144:147], v[194:197], v[44:47]
	v_mfma_f32_16x16x32_bf16 v[40:43], v[160:163], v[194:197], v[40:43]
	v_mfma_f32_16x16x32_bf16 v[28:31], v[144:147], v[202:205], v[28:31]
	v_mfma_f32_16x16x32_bf16 v[24:27], v[160:163], v[202:205], v[24:27]
	v_mfma_f32_16x16x32_bf16 v[12:15], v[144:147], v[210:213], v[12:15]
	v_mfma_f32_16x16x32_bf16 v[8:11], v[160:163], v[210:213], v[8:11]
	v_mfma_f32_16x16x32_bf16 v[60:63], v[148:151], v[190:193], v[60:63]
	v_mfma_f32_16x16x32_bf16 v[56:59], v[164:167], v[190:193], v[56:59]
	v_mfma_f32_16x16x32_bf16 v[44:47], v[148:151], v[198:201], v[44:47]
	v_mfma_f32_16x16x32_bf16 v[40:43], v[164:167], v[198:201], v[40:43]
	v_mfma_f32_16x16x32_bf16 v[28:31], v[148:151], v[206:209], v[28:31]
	v_mfma_f32_16x16x32_bf16 v[24:27], v[164:167], v[206:209], v[24:27]
	v_mfma_f32_16x16x32_bf16 v[12:15], v[148:151], v[214:217], v[12:15]
	v_mfma_f32_16x16x32_bf16 v[8:11], v[164:167], v[214:217], v[8:11]
	s_setprio 0
	s_setprio 1
	v_mfma_f32_16x16x32_bf16 v[52:55], v[170:173], v[186:189], v[52:55]
	v_mfma_f32_16x16x32_bf16 v[48:51], v[178:181], v[186:189], v[48:51]
	v_mfma_f32_16x16x32_bf16 v[36:39], v[170:173], v[194:197], v[36:39]
	v_mfma_f32_16x16x32_bf16 v[32:35], v[178:181], v[194:197], v[32:35]
	v_mfma_f32_16x16x32_bf16 v[20:23], v[170:173], v[202:205], v[20:23]
	v_mfma_f32_16x16x32_bf16 v[16:19], v[178:181], v[202:205], v[16:19]
	v_mfma_f32_16x16x32_bf16 v[4:7], v[170:173], v[210:213], v[4:7]
	v_mfma_f32_16x16x32_bf16 v[0:3], v[178:181], v[210:213], v[0:3]
	v_mfma_f32_16x16x32_bf16 v[52:55], v[174:177], v[190:193], v[52:55]
	v_mfma_f32_16x16x32_bf16 v[48:51], v[182:185], v[190:193], v[48:51]
	v_mfma_f32_16x16x32_bf16 v[36:39], v[174:177], v[198:201], v[36:39]
	v_mfma_f32_16x16x32_bf16 v[32:35], v[182:185], v[198:201], v[32:35]
	v_mfma_f32_16x16x32_bf16 v[20:23], v[174:177], v[206:209], v[20:23]
	v_mfma_f32_16x16x32_bf16 v[16:19], v[182:185], v[206:209], v[16:19]
	v_mfma_f32_16x16x32_bf16 v[4:7], v[174:177], v[214:217], v[4:7]
	v_mfma_f32_16x16x32_bf16 v[0:3], v[182:185], v[214:217], v[0:3]
	s_setprio 0
	s_barrier
	s_add_i32 s64, 0, 0x18000
	v_add_u32_e32 v159, s64, v153
	s_add_i32 s65, 0, 0x1c000
	ds_read_b128 v[144:147], v159
	ds_read_b128 v[148:151], v159 offset:1024
	ds_read_b128 v[160:163], v159 offset:2048
	ds_read_b128 v[164:167], v159 offset:3072
	v_add_u32_e32 v159, s65, v153
	ds_read_b128 v[170:173], v159
	ds_read_b128 v[174:177], v159 offset:1024
	ds_read_b128 v[178:181], v159 offset:2048
	ds_read_b128 v[182:185], v159 offset:3072
	s_add_u32 s42, s42, 0x40000
	s_addc_u32 s43, s43, 0
	s_mov_b32 m0, s49
	ds_read_b128 v[186:189], v157 offset:32768
	ds_read_b128 v[190:193], v157 offset:33792
	ds_read_b128 v[194:197], v157 offset:34816
	ds_read_b128 v[198:201], v157 offset:35840
	ds_read_b128 v[202:205], v157 offset:36864
	ds_read_b128 v[206:209], v157 offset:37888
	ds_read_b128 v[210:213], v157 offset:38912
	ds_read_b128 v[214:217], v157 offset:39936
	global_load_lds_dwordx4 v134, s[42:43]
	s_mov_b32 m0, s50
	s_nop 0
	global_load_lds_dwordx4 v130, s[42:43]
	s_waitcnt vmcnt(8)
	s_waitcnt lgkmcnt(0)
	s_barrier
	s_setprio 1
	s_waitcnt lgkmcnt(0)
	v_mfma_f32_16x16x32_bf16 v[124:127], v[144:147], v[186:189], v[124:127]
	v_mfma_f32_16x16x32_bf16 v[120:123], v[160:163], v[186:189], v[120:123]
	v_mfma_f32_16x16x32_bf16 v[108:111], v[144:147], v[194:197], v[108:111]
	v_mfma_f32_16x16x32_bf16 v[104:107], v[160:163], v[194:197], v[104:107]
	v_mfma_f32_16x16x32_bf16 v[92:95], v[144:147], v[202:205], v[92:95]
	v_mfma_f32_16x16x32_bf16 v[88:91], v[160:163], v[202:205], v[88:91]
	v_mfma_f32_16x16x32_bf16 v[76:79], v[144:147], v[210:213], v[76:79]
	v_mfma_f32_16x16x32_bf16 v[72:75], v[160:163], v[210:213], v[72:75]
	v_mfma_f32_16x16x32_bf16 v[124:127], v[148:151], v[190:193], v[124:127]
	v_mfma_f32_16x16x32_bf16 v[120:123], v[164:167], v[190:193], v[120:123]
	v_mfma_f32_16x16x32_bf16 v[108:111], v[148:151], v[198:201], v[108:111]
	v_mfma_f32_16x16x32_bf16 v[104:107], v[164:167], v[198:201], v[104:107]
	v_mfma_f32_16x16x32_bf16 v[92:95], v[148:151], v[206:209], v[92:95]
	v_mfma_f32_16x16x32_bf16 v[88:91], v[164:167], v[206:209], v[88:91]
	v_mfma_f32_16x16x32_bf16 v[76:79], v[148:151], v[214:217], v[76:79]
	v_mfma_f32_16x16x32_bf16 v[72:75], v[164:167], v[214:217], v[72:75]
	s_setprio 0
	s_setprio 1
	v_mfma_f32_16x16x32_bf16 v[116:119], v[170:173], v[186:189], v[116:119]
	v_mfma_f32_16x16x32_bf16 v[112:115], v[178:181], v[186:189], v[112:115]
	v_mfma_f32_16x16x32_bf16 v[100:103], v[170:173], v[194:197], v[100:103]
	v_mfma_f32_16x16x32_bf16 v[96:99], v[178:181], v[194:197], v[96:99]
	v_mfma_f32_16x16x32_bf16 v[84:87], v[170:173], v[202:205], v[84:87]
	v_mfma_f32_16x16x32_bf16 v[80:83], v[178:181], v[202:205], v[80:83]
	v_mfma_f32_16x16x32_bf16 v[68:71], v[170:173], v[210:213], v[68:71]
	v_mfma_f32_16x16x32_bf16 v[64:67], v[178:181], v[210:213], v[64:67]
	v_mfma_f32_16x16x32_bf16 v[116:119], v[174:177], v[190:193], v[116:119]
	v_mfma_f32_16x16x32_bf16 v[112:115], v[182:185], v[190:193], v[112:115]
	v_mfma_f32_16x16x32_bf16 v[100:103], v[174:177], v[198:201], v[100:103]
	v_mfma_f32_16x16x32_bf16 v[96:99], v[182:185], v[198:201], v[96:99]
	v_mfma_f32_16x16x32_bf16 v[84:87], v[174:177], v[206:209], v[84:87]
	v_mfma_f32_16x16x32_bf16 v[80:83], v[182:185], v[206:209], v[80:83]
	v_mfma_f32_16x16x32_bf16 v[68:71], v[174:177], v[214:217], v[68:71]
	v_mfma_f32_16x16x32_bf16 v[64:67], v[182:185], v[214:217], v[64:67]
	s_setprio 0
	s_barrier
	s_add_i32 s42, s64, s45
	s_add_u32 s98, s40, s14
	s_addc_u32 s99, s41, s15
	s_mov_b32 m0, s42
	ds_read_b128 v[186:189], v157 offset:49152
	ds_read_b128 v[190:193], v157 offset:50176
	ds_read_b128 v[194:197], v157 offset:51200
	ds_read_b128 v[198:201], v157 offset:52224
	ds_read_b128 v[202:205], v157 offset:53248
	ds_read_b128 v[206:209], v157 offset:54272
	ds_read_b128 v[210:213], v157 offset:55296
	ds_read_b128 v[214:217], v157 offset:56320
	global_load_lds_dwordx4 v132, s[98:99]
	s_add_i32 m0, s42, 0x2000
	s_add_u32 s40, s40, 0x40080
	s_addc_u32 s41, s41, 0
	s_add_i32 s42, s65, s45
	global_load_lds_dwordx4 v128, s[98:99]
	s_mov_b32 m0, s42
	s_nop 0
	global_load_lds_dwordx4 v132, s[40:41]
	s_add_i32 m0, s42, 0x2000
	s_nop 0
	global_load_lds_dwordx4 v128, s[40:41]
	s_mov_b32 m0, s52
	s_nop 0
	global_load_lds_dwordx4 v134, vcc
	s_mov_b32 m0, s53
	s_nop 0
	global_load_lds_dwordx4 v130, vcc
	s_waitcnt vmcnt(8)
	s_waitcnt lgkmcnt(0)
	s_barrier
	s_setprio 1
	s_waitcnt lgkmcnt(0)
	v_mfma_f32_16x16x32_bf16 v[60:63], v[144:147], v[186:189], v[60:63]
	v_mfma_f32_16x16x32_bf16 v[56:59], v[160:163], v[186:189], v[56:59]
	v_mfma_f32_16x16x32_bf16 v[44:47], v[144:147], v[194:197], v[44:47]
	v_mfma_f32_16x16x32_bf16 v[40:43], v[160:163], v[194:197], v[40:43]
	v_mfma_f32_16x16x32_bf16 v[28:31], v[144:147], v[202:205], v[28:31]
	v_mfma_f32_16x16x32_bf16 v[24:27], v[160:163], v[202:205], v[24:27]
	v_mfma_f32_16x16x32_bf16 v[12:15], v[144:147], v[210:213], v[12:15]
	v_mfma_f32_16x16x32_bf16 v[8:11], v[160:163], v[210:213], v[8:11]
	v_mfma_f32_16x16x32_bf16 v[60:63], v[148:151], v[190:193], v[60:63]
	v_mfma_f32_16x16x32_bf16 v[56:59], v[164:167], v[190:193], v[56:59]
	v_mfma_f32_16x16x32_bf16 v[44:47], v[148:151], v[198:201], v[44:47]
	v_mfma_f32_16x16x32_bf16 v[40:43], v[164:167], v[198:201], v[40:43]
	v_mfma_f32_16x16x32_bf16 v[28:31], v[148:151], v[206:209], v[28:31]
	v_mfma_f32_16x16x32_bf16 v[24:27], v[164:167], v[206:209], v[24:27]
	v_mfma_f32_16x16x32_bf16 v[12:15], v[148:151], v[214:217], v[12:15]
	v_mfma_f32_16x16x32_bf16 v[8:11], v[164:167], v[214:217], v[8:11]
	s_setprio 0
	s_setprio 1
	v_mfma_f32_16x16x32_bf16 v[52:55], v[170:173], v[186:189], v[52:55]
	v_mfma_f32_16x16x32_bf16 v[48:51], v[178:181], v[186:189], v[48:51]
	v_mfma_f32_16x16x32_bf16 v[36:39], v[170:173], v[194:197], v[36:39]
	v_mfma_f32_16x16x32_bf16 v[32:35], v[178:181], v[194:197], v[32:35]
	v_mfma_f32_16x16x32_bf16 v[20:23], v[170:173], v[202:205], v[20:23]
	v_mfma_f32_16x16x32_bf16 v[16:19], v[178:181], v[202:205], v[16:19]
	v_mfma_f32_16x16x32_bf16 v[4:7], v[170:173], v[210:213], v[4:7]
	v_mfma_f32_16x16x32_bf16 v[0:3], v[178:181], v[210:213], v[0:3]
	v_mfma_f32_16x16x32_bf16 v[52:55], v[174:177], v[190:193], v[52:55]
	v_mfma_f32_16x16x32_bf16 v[48:51], v[182:185], v[190:193], v[48:51]
	v_mfma_f32_16x16x32_bf16 v[36:39], v[174:177], v[198:201], v[36:39]
	v_mfma_f32_16x16x32_bf16 v[32:35], v[182:185], v[198:201], v[32:35]
	v_mfma_f32_16x16x32_bf16 v[20:23], v[174:177], v[206:209], v[20:23]
	v_mfma_f32_16x16x32_bf16 v[16:19], v[182:185], v[206:209], v[16:19]
	v_mfma_f32_16x16x32_bf16 v[4:7], v[174:177], v[214:217], v[4:7]
	v_mfma_f32_16x16x32_bf16 v[0:3], v[182:185], v[214:217], v[0:3]
	s_setprio 0
	s_barrier
	s_add_i32 s63, s63, 2
	s_add_u32 s38, s38, 0x100
	s_addc_u32 s39, s39, 0
	s_add_u32 s61, s61, 0x100
	s_addc_u32 s62, s62, 0
	s_cmp_gt_u32 s63, 13
	s_cbranch_scc0 .LBB0_544
	s_and_b64 vcc, exec, s[16:17]
	s_cbranch_vccz .LBB0_547
	s_barrier
